# v30: v29 + the LN2 row-absmax butterflies (moe + dense) as DPP / permlane swaps too (no LDS crossbar round trips left in the LN2 row loops)
# baseline (speedup 1.0000x reference)
; #define LAS __attribute__((address_space(3)))
; __device__ __forceinline__ unsigned pk2(float lo, float hi) { return cvt_pk_bf16(lo, hi); }
; __device__ __forceinline__ void h_store_i8(const f32x4 (&hv)[4], float am, signed char* dst, float* scl_out, int lane) {
; #pragma unroll
;     for (int o = 1; o < 64; o <<= 1) am = fmaxf(am, __shfl_xor(am, o));
;     const float scl = fmaxf(am, 1e-30f) * (1.0f / 127.0f), inv = 1.0f / scl;
;     unsigned* q8 = (unsigned*)dst;
; #pragma unroll
;     for (int jj = 0; jj < 4; ++jj) { unsigned pk = 0;
; #pragma unroll
;         for (int i = 0; i < 4; ++i) pk |= ((unsigned)(int)rintf(hv[jj][i] * inv) & 0xffu) << (8 * i);
;         q8[64 * jj] = pk; }
;     if (lane == 0) *scl_out = scl;
; }
; template <int MODE, bool ROUTE, int H8> ...
;     ...
;             f32x4 hv[4];
; #pragma unroll
;             for (int jj = 0; jj < 4; ++jj) {
;                 const f32x4 xn = v[jj] * rstd * g4[jj] + b4[jj];
;                 if (xout16) __builtin_nontemporal_store(__builtin_bit_cast(u32x2, __builtin_convertvector(xn, f16x4_t)), (u32x2*)(XH + (size_t)row * D + 4 * F.lane + 256 * jj));
;                 else __builtin_nontemporal_store(xn, (f32x4*)(orow + 256 * jj));
;                 if (next_mod) {
;                     const f32x4 h = xn * (1.0f + nsc[jj]) + nsh[jj];
;                     hv[jj] = h;
;                     if (H8 == 0) h8[64 * jj] = (unsigned long long)pk2(h[0], h[1]) | ((unsigned long long)pk2(h[2], h[3]) << 32);
;                     if (ROUTE) {
; #pragma unroll
;                         for (int i = 0; i < 4; ++i) { const LAS f32x4* wp = (const LAS f32x4*)(wr_l + (4 * F.lane + 256 * jj + i) * 8); const f32x4 wa = wp[0], wb = wp[1];
;                             lg[0] += h[i] * wa[0]; lg[1] += h[i] * wa[1]; lg[2] += h[i] * wa[2]; lg[3] += h[i] * wa[3]; lg[4] += h[i] * wb[0]; lg[5] += h[i] * wb[1]; lg[6] += h[i] * wb[2]; lg[7] += h[i] * wb[3]; }
;                     }
;                 }
;             }
;             if (H8 == 2 && next_mod) {
;                 float am = 0.f;
; #pragma unroll
;                 for (int jj = 0; jj < 4; ++jj) am = fmaxf(fmaxf(am, fmaxf(fabsf(hv[jj][0]), fabsf(hv[jj][1]))), fmaxf(fabsf(hv[jj][2]), fabsf(hv[jj][3])));
;                 h_store_i8(hv, am, (signed char*)HB + (size_t)row * D + 4 * F.lane, (float*)(F.ws + WS_HSC) + row, F.lane);
.LBB0_1258:
	v_pk_fma_f32 v[86:87], v[114:115], v[86:87], v[60:61]
	v_pk_fma_f32 v[84:85], v[112:113], v[84:85], v[58:59]
	v_cndmask_b32_e64 v66, v86, v4, s[38:39]
	v_cndmask_b32_e64 v101, v87, v5, s[38:39]
	v_cndmask_b32_e64 v152, v84, v2, s[38:39]
	v_cndmask_b32_e64 v153, v85, v3, s[38:39]
	v_pk_fma_f32 v[84:85], v[116:117], v[90:91], v[56:57]
	v_pk_fma_f32 v[86:87], v[110:111], v[88:89], v[54:55]
	v_cndmask_b32_e64 v88, v85, v9, s[38:39]
	v_cndmask_b32_e64 v89, v84, v8, s[38:39]
	v_cndmask_b32_e64 v90, v101, v5, s[38:39]
	v_cndmask_b32_e64 v66, v66, v4, s[38:39]
	v_cndmask_b32_e64 v91, v87, v7, s[38:39]
	v_cndmask_b32_e64 v101, v86, v6, s[38:39]
	v_cndmask_b32_e64 v153, v153, v3, s[38:39]
	v_cndmask_b32_e64 v152, v152, v2, s[38:39]
	v_pk_fma_f32 v[84:85], v[122:123], v[94:95], v[78:79]
	v_pk_fma_f32 v[86:87], v[120:121], v[92:93], v[76:77]
	v_cndmask_b32_e64 v66, v66, v4, s[38:39]
	v_cndmask_b32_e64 v90, v90, v5, s[38:39]
	v_cndmask_b32_e64 v89, v89, v8, s[38:39]
	v_cndmask_b32_e64 v88, v88, v9, s[38:39]
	v_cndmask_b32_e64 v92, v84, v12, s[38:39]
	v_cndmask_b32_e64 v93, v85, v13, s[38:39]
	v_cndmask_b32_e64 v94, v152, v2, s[38:39]
	v_cndmask_b32_e64 v95, v153, v3, s[38:39]
	v_cndmask_b32_e64 v101, v101, v6, s[38:39]
	v_cndmask_b32_e64 v91, v91, v7, s[38:39]
	v_cndmask_b32_e64 v152, v86, v10, s[38:39]
	v_cndmask_b32_e64 v153, v87, v11, s[38:39]
	v_pk_fma_f32 v[84:85], v[124:125], v[98:99], v[74:75]
	v_pk_fma_f32 v[86:87], v[118:119], v[96:97], v[72:73]
	v_cndmask_b32_e64 v17, v85, v17, s[38:39]
	v_cndmask_b32_e64 v16, v84, v16, s[38:39]
	v_cndmask_b32_e64 v13, v93, v13, s[38:39]
	v_cndmask_b32_e64 v12, v92, v12, s[38:39]
	v_cndmask_b32_e64 v9, v88, v9, s[38:39]
	v_cndmask_b32_e64 v8, v89, v8, s[38:39]
	v_cndmask_b32_e64 v5, v90, v5, s[38:39]
	v_cndmask_b32_e64 v4, v66, v4, s[38:39]
	v_cndmask_b32_e64 v15, v87, v15, s[38:39]
	v_cndmask_b32_e64 v14, v86, v14, s[38:39]
	v_cndmask_b32_e64 v11, v153, v11, s[38:39]
	v_cndmask_b32_e64 v10, v152, v10, s[38:39]
	v_cndmask_b32_e64 v7, v91, v7, s[38:39]
	v_cndmask_b32_e64 v6, v101, v6, s[38:39]
	v_cndmask_b32_e64 v3, v95, v3, s[38:39]
	v_cndmask_b32_e64 v2, v94, v2, s[38:39]
	s_and_b64 vcc, exec, s[0:1]
	s_cbranch_vccz .Lmy_ln2m_tail4
	v_max_f32_e64 v66, |v3|, |v3|
	v_max_f32_e64 v84, |v2|, |v2|
	v_max_f32_e32 v66, v84, v66
	v_max_f32_e64 v84, |v5|, |v5|
	v_max_f32_e64 v85, |v4|, |v4|
	v_max_f32_e32 v84, v85, v84
	v_max3_f32 v66, v66, 0, v84
	v_max_f32_e64 v84, |v7|, |v7|
	v_max_f32_e64 v85, |v6|, |v6|
	v_max_f32_e32 v84, v85, v84
	v_max_f32_e64 v85, |v9|, |v9|
	v_max_f32_e64 v86, |v8|, |v8|
	v_max_f32_e32 v85, v86, v85
	v_max3_f32 v66, v66, v84, v85
	v_max_f32_e64 v84, |v11|, |v11|
	v_max_f32_e64 v85, |v10|, |v10|
	v_max_f32_e32 v84, v85, v84
	v_max_f32_e64 v85, |v13|, |v13|
	v_max_f32_e64 v86, |v12|, |v12|
	v_max_f32_e32 v85, v86, v85
	v_max3_f32 v66, v66, v84, v85
	v_max_f32_e64 v84, |v15|, |v15|
	v_max_f32_e64 v85, |v14|, |v14|
	v_max_f32_e32 v84, v85, v84
	v_max_f32_e64 v85, |v17|, |v17|
	v_max_f32_e64 v86, |v16|, |v16|
	v_max_f32_e32 v85, v86, v85
	v_max3_f32 v66, v66, v84, v85
	s_nop 1
	s_mov_b32 s4, 0xda24260
	s_lshl_b64 s[24:25], s[46:47], 10
	v_lshl_add_u64 v[84:85], v[106:107], 0, s[24:25]
	s_waitcnt lgkmcnt(0)
	v_max_f32_e32 v86, v86, v86
	v_max_f32_dpp v66, v66, v66 quad_perm:[1,0,3,2] row_mask:0xf bank_mask:0xf
	s_nop 1
	s_waitcnt lgkmcnt(0)
	v_max_f32_e32 v86, v86, v86
	v_max_f32_dpp v66, v66, v66 quad_perm:[2,3,0,1] row_mask:0xf bank_mask:0xf
	s_nop 1
	s_waitcnt lgkmcnt(0)
	v_max_f32_e32 v86, v86, v86
	v_max_f32_dpp v66, v66, v66 row_half_mirror row_mask:0xf bank_mask:0xf
	s_nop 1
	s_waitcnt lgkmcnt(0)
	v_max_f32_e32 v86, v86, v86
	v_max_f32_dpp v66, v66, v66 row_mirror row_mask:0xf bank_mask:0xf
	v_mov_b32_e32 v86, v66
	s_nop 1
	v_permlane16_swap_b32_e32 v86, v66
	s_waitcnt lgkmcnt(0)
	v_max_f32_e32 v86, v86, v86
	v_max_f32_e32 v66, v66, v86
	v_mov_b32_e32 v86, v66
	s_nop 1
	v_permlane32_swap_b32_e32 v86, v66
	s_waitcnt lgkmcnt(0)
	v_max3_f32 v66, v66, v86, s4
	v_mul_f32_e32 v66, 0x3c010204, v66
	v_div_scale_f32 v86, s[24:25], v66, v66, 1.0
	v_rcp_f32_e32 v87, v86
	s_nop 0
	v_fma_f32 v88, -v86, v87, 1.0
	v_fmac_f32_e32 v87, v88, v87
	v_div_scale_f32 v88, vcc, 1.0, v66, 1.0
	v_mul_f32_e32 v89, v88, v87
	v_fma_f32 v90, -v86, v89, v88
	v_fmac_f32_e32 v89, v90, v87
	v_fma_f32 v86, -v86, v89, v88
	v_div_fmas_f32 v86, v86, v87, v89
	v_div_fixup_f32 v86, v86, v66, 1.0
	v_mul_f32_e32 v88, v3, v86
	v_mul_f32_e32 v87, v2, v86
	v_rndne_f32_e32 v88, v88
	v_mul_f32_e32 v89, v4, v86
	v_mul_f32_e32 v90, v5, v86
	v_rndne_f32_e32 v87, v87
	v_cvt_i32_f32_e32 v88, v88
	v_rndne_f32_e32 v89, v89
	v_rndne_f32_e32 v90, v90
	v_cvt_i32_f32_e32 v87, v87
	v_cvt_i32_f32_sdwa v89, v89 dst_sel:WORD_1 dst_unused:UNUSED_PAD src0_sel:DWORD
	v_cvt_i32_f32_e32 v90, v90
	v_lshlrev_b32_e32 v88, 8, v88
	v_and_b32_e32 v88, 0xff00, v88
	v_and_b32_e32 v89, 0xff0000, v89
	v_perm_b32 v87, v90, v87, s84
	v_or3_b32 v87, v87, v88, v89
	v_mul_f32_e32 v88, v7, v86
	global_store_dword v[84:85], v87, off
	v_mul_f32_e32 v87, v6, v86
	v_rndne_f32_e32 v88, v88
	v_mul_f32_e32 v89, v8, v86
	v_mul_f32_e32 v90, v9, v86
	v_rndne_f32_e32 v87, v87
	v_cvt_i32_f32_e32 v88, v88
	v_rndne_f32_e32 v89, v89
	v_rndne_f32_e32 v90, v90
	v_cvt_i32_f32_e32 v87, v87
	v_cvt_i32_f32_sdwa v89, v89 dst_sel:WORD_1 dst_unused:UNUSED_PAD src0_sel:DWORD
	v_cvt_i32_f32_e32 v90, v90
	v_lshlrev_b32_e32 v88, 8, v88
	v_and_b32_e32 v88, 0xff00, v88
	v_and_b32_e32 v89, 0xff0000, v89
	v_perm_b32 v87, v90, v87, s84
	v_or3_b32 v87, v87, v88, v89
	v_mul_f32_e32 v88, v11, v86
	global_store_dword v[84:85], v87, off offset:256
	v_mul_f32_e32 v87, v10, v86
	v_rndne_f32_e32 v88, v88
	v_mul_f32_e32 v89, v12, v86
	v_mul_f32_e32 v90, v13, v86
	v_rndne_f32_e32 v87, v87
	v_cvt_i32_f32_e32 v88, v88
	v_rndne_f32_e32 v89, v89
	v_rndne_f32_e32 v90, v90
	v_cvt_i32_f32_e32 v87, v87
	v_cvt_i32_f32_sdwa v89, v89 dst_sel:WORD_1 dst_unused:UNUSED_PAD src0_sel:DWORD
	v_cvt_i32_f32_e32 v90, v90
	v_lshlrev_b32_e32 v88, 8, v88
	v_and_b32_e32 v88, 0xff00, v88
	v_and_b32_e32 v89, 0xff0000, v89
	v_perm_b32 v87, v90, v87, s84
	v_or3_b32 v87, v87, v88, v89
	v_mul_f32_e32 v88, v15, v86
	global_store_dword v[84:85], v87, off offset:512
	v_mul_f32_e32 v87, v14, v86
	v_rndne_f32_e32 v88, v88
	v_mul_f32_e32 v89, v16, v86
	v_mul_f32_e32 v86, v17, v86
	v_rndne_f32_e32 v87, v87
	v_cvt_i32_f32_e32 v88, v88
	v_rndne_f32_e32 v89, v89
	v_rndne_f32_e32 v86, v86
	v_cvt_i32_f32_e32 v87, v87
	v_cvt_i32_f32_sdwa v89, v89 dst_sel:WORD_1 dst_unused:UNUSED_PAD src0_sel:DWORD
	v_cvt_i32_f32_e32 v86, v86
	v_lshlrev_b32_e32 v88, 8, v88
	v_and_b32_e32 v88, 0xff00, v88
	v_and_b32_e32 v89, 0xff0000, v89
	v_perm_b32 v86, v86, v87, s84
	v_or3_b32 v86, v86, v88, v89
	global_store_dword v[84:85], v86, off offset:768
	s_and_saveexec_b64 s[24:25], s[40:41]
	s_cbranch_execz .LBB0_1238
	s_lshl_b64 s[42:43], s[46:47], 2
	s_add_u32 s42, s52, s42
	s_addc_u32 s43, s53, s43
	global_store_dword v67, v66, s[42:43]
	s_branch .Lmy_ln2m_tail9

; #define LAS __attribute__((address_space(3)))
; __device__ __forceinline__ unsigned pk2(float lo, float hi) { return cvt_pk_bf16(lo, hi); }
; __device__ __forceinline__ void h_store_i8(const f32x4 (&hv)[4], float am, signed char* dst, float* scl_out, int lane) {
; #pragma unroll
;     for (int o = 1; o < 64; o <<= 1) am = fmaxf(am, __shfl_xor(am, o));
;     const float scl = fmaxf(am, 1e-30f) * (1.0f / 127.0f), inv = 1.0f / scl;
;     unsigned* q8 = (unsigned*)dst;
; #pragma unroll
;     for (int jj = 0; jj < 4; ++jj) { unsigned pk = 0;
; #pragma unroll
;         for (int i = 0; i < 4; ++i) pk |= ((unsigned)(int)rintf(hv[jj][i] * inv) & 0xffu) << (8 * i);
;         q8[64 * jj] = pk; }
;     if (lane == 0) *scl_out = scl;
; }
; template <int MODE, bool ROUTE, int H8> ...
;     ...
;             f32x4 hv[4];
; #pragma unroll
;             for (int jj = 0; jj < 4; ++jj) {
;                 const f32x4 xn = v[jj] * rstd * g4[jj] + b4[jj];
;                 if (xout16) __builtin_nontemporal_store(__builtin_bit_cast(u32x2, __builtin_convertvector(xn, f16x4_t)), (u32x2*)(XH + (size_t)row * D + 4 * F.lane + 256 * jj));
;                 else __builtin_nontemporal_store(xn, (f32x4*)(orow + 256 * jj));
;                 if (next_mod) {
;                     const f32x4 h = xn * (1.0f + nsc[jj]) + nsh[jj];
;                     hv[jj] = h;
;                     if (H8 == 0) h8[64 * jj] = (unsigned long long)pk2(h[0], h[1]) | ((unsigned long long)pk2(h[2], h[3]) << 32);
;                     if (ROUTE) {
; #pragma unroll
;                         for (int i = 0; i < 4; ++i) { const LAS f32x4* wp = (const LAS f32x4*)(wr_l + (4 * F.lane + 256 * jj + i) * 8); const f32x4 wa = wp[0], wb = wp[1];
;                             lg[0] += h[i] * wa[0]; lg[1] += h[i] * wa[1]; lg[2] += h[i] * wa[2]; lg[3] += h[i] * wa[3]; lg[4] += h[i] * wb[0]; lg[5] += h[i] * wb[1]; lg[6] += h[i] * wb[2]; lg[7] += h[i] * wb[3]; }
;                     }
;                 }
;             }
;             if (H8 == 2 && next_mod) {
;                 float am = 0.f;
; #pragma unroll
;                 for (int jj = 0; jj < 4; ++jj) am = fmaxf(fmaxf(am, fmaxf(fabsf(hv[jj][0]), fabsf(hv[jj][1]))), fmaxf(fabsf(hv[jj][2]), fabsf(hv[jj][3])));
;                 h_store_i8(hv, am, (signed char*)HB + (size_t)row * D + 4 * F.lane, (float*)(F.ws + WS_HSC) + row, F.lane);
.LBB0_1296:
	v_pk_fma_f32 v[86:87], v[114:115], v[86:87], v[60:61]
	v_pk_fma_f32 v[84:85], v[112:113], v[84:85], v[58:59]
	v_cndmask_b32_e64 v66, v86, v4, s[38:39]
	v_cndmask_b32_e64 v101, v87, v5, s[38:39]
	v_cndmask_b32_e64 v142, v84, v2, s[38:39]
	v_cndmask_b32_e64 v143, v85, v3, s[38:39]
	v_pk_fma_f32 v[84:85], v[116:117], v[90:91], v[56:57]
	v_pk_fma_f32 v[86:87], v[110:111], v[88:89], v[54:55]
	v_cndmask_b32_e64 v88, v85, v9, s[38:39]
	v_cndmask_b32_e64 v89, v84, v8, s[38:39]
	v_cndmask_b32_e64 v90, v101, v5, s[38:39]
	v_cndmask_b32_e64 v66, v66, v4, s[38:39]
	v_cndmask_b32_e64 v91, v87, v7, s[38:39]
	v_cndmask_b32_e64 v101, v86, v6, s[38:39]
	v_cndmask_b32_e64 v143, v143, v3, s[38:39]
	v_cndmask_b32_e64 v142, v142, v2, s[38:39]
	v_pk_fma_f32 v[84:85], v[122:123], v[94:95], v[78:79]
	v_pk_fma_f32 v[86:87], v[120:121], v[92:93], v[76:77]
	v_cndmask_b32_e64 v66, v66, v4, s[38:39]
	v_cndmask_b32_e64 v90, v90, v5, s[38:39]
	v_cndmask_b32_e64 v89, v89, v8, s[38:39]
	v_cndmask_b32_e64 v88, v88, v9, s[38:39]
	v_cndmask_b32_e64 v92, v84, v12, s[38:39]
	v_cndmask_b32_e64 v93, v85, v13, s[38:39]
	v_cndmask_b32_e64 v94, v142, v2, s[38:39]
	v_cndmask_b32_e64 v95, v143, v3, s[38:39]
	v_cndmask_b32_e64 v101, v101, v6, s[38:39]
	v_cndmask_b32_e64 v91, v91, v7, s[38:39]
	v_cndmask_b32_e64 v142, v86, v10, s[38:39]
	v_cndmask_b32_e64 v143, v87, v11, s[38:39]
	v_pk_fma_f32 v[84:85], v[124:125], v[98:99], v[74:75]
	v_pk_fma_f32 v[86:87], v[118:119], v[96:97], v[72:73]
	v_cndmask_b32_e64 v17, v85, v17, s[38:39]
	v_cndmask_b32_e64 v16, v84, v16, s[38:39]
	v_cndmask_b32_e64 v13, v93, v13, s[38:39]
	v_cndmask_b32_e64 v12, v92, v12, s[38:39]
	v_cndmask_b32_e64 v9, v88, v9, s[38:39]
	v_cndmask_b32_e64 v8, v89, v8, s[38:39]
	v_cndmask_b32_e64 v5, v90, v5, s[38:39]
	v_cndmask_b32_e64 v4, v66, v4, s[38:39]
	v_cndmask_b32_e64 v15, v87, v15, s[38:39]
	v_cndmask_b32_e64 v14, v86, v14, s[38:39]
	v_cndmask_b32_e64 v11, v143, v11, s[38:39]
	v_cndmask_b32_e64 v10, v142, v10, s[38:39]
	v_cndmask_b32_e64 v7, v91, v7, s[38:39]
	v_cndmask_b32_e64 v6, v101, v6, s[38:39]
	v_cndmask_b32_e64 v3, v95, v3, s[38:39]
	v_cndmask_b32_e64 v2, v94, v2, s[38:39]
	s_and_b64 vcc, exec, s[0:1]
	s_cbranch_vccz .Lmy_ln2d_tail4
	v_max_f32_e64 v66, |v3|, |v3|
	v_max_f32_e64 v84, |v2|, |v2|
	v_max_f32_e32 v66, v84, v66
	v_max_f32_e64 v84, |v5|, |v5|
	v_max_f32_e64 v85, |v4|, |v4|
	v_max_f32_e32 v84, v85, v84
	v_max3_f32 v66, v66, 0, v84
	v_max_f32_e64 v84, |v7|, |v7|
	v_max_f32_e64 v85, |v6|, |v6|
	v_max_f32_e32 v84, v85, v84
	v_max_f32_e64 v85, |v9|, |v9|
	v_max_f32_e64 v86, |v8|, |v8|
	v_max_f32_e32 v85, v86, v85
	v_max3_f32 v66, v66, v84, v85
	v_max_f32_e64 v84, |v11|, |v11|
	v_max_f32_e64 v85, |v10|, |v10|
	v_max_f32_e32 v84, v85, v84
	v_max_f32_e64 v85, |v13|, |v13|
	v_max_f32_e64 v86, |v12|, |v12|
	v_max_f32_e32 v85, v86, v85
	v_max3_f32 v66, v66, v84, v85
	v_max_f32_e64 v84, |v15|, |v15|
	v_max_f32_e64 v85, |v14|, |v14|
	v_max_f32_e32 v84, v85, v84
	v_max_f32_e64 v85, |v17|, |v17|
	v_max_f32_e64 v86, |v16|, |v16|
	v_max_f32_e32 v85, v86, v85
	v_max3_f32 v66, v66, v84, v85
	s_nop 1
	s_lshl_b64 s[2:3], s[10:11], 10
	v_lshl_add_u64 v[84:85], v[108:109], 0, s[2:3]
	s_mov_b32 s2, 0xda24260
	s_waitcnt lgkmcnt(0)
	v_max_f32_e32 v86, v86, v86
	v_max_f32_dpp v66, v66, v66 quad_perm:[1,0,3,2] row_mask:0xf bank_mask:0xf
	s_nop 1
	s_waitcnt lgkmcnt(0)
	v_max_f32_e32 v86, v86, v86
	v_max_f32_dpp v66, v66, v66 quad_perm:[2,3,0,1] row_mask:0xf bank_mask:0xf
	s_nop 1
	s_waitcnt lgkmcnt(0)
	v_max_f32_e32 v86, v86, v86
	v_max_f32_dpp v66, v66, v66 row_half_mirror row_mask:0xf bank_mask:0xf
	s_nop 1
	s_waitcnt lgkmcnt(0)
	v_max_f32_e32 v86, v86, v86
	v_max_f32_dpp v66, v66, v66 row_mirror row_mask:0xf bank_mask:0xf
	v_mov_b32_e32 v86, v66
	s_nop 1
	v_permlane16_swap_b32_e32 v86, v66
	s_waitcnt lgkmcnt(0)
	v_max_f32_e32 v86, v86, v86
	v_max_f32_e32 v66, v66, v86
	v_mov_b32_e32 v86, v66
	s_nop 1
	v_permlane32_swap_b32_e32 v86, v66
	s_waitcnt lgkmcnt(0)
	v_max3_f32 v66, v66, v86, s2
	v_mul_f32_e32 v66, 0x3c010204, v66
	v_div_scale_f32 v86, s[2:3], v66, v66, 1.0
	v_rcp_f32_e32 v87, v86
	s_nop 0
	v_fma_f32 v88, -v86, v87, 1.0
	v_fmac_f32_e32 v87, v88, v87
	v_div_scale_f32 v88, vcc, 1.0, v66, 1.0
	v_mul_f32_e32 v89, v88, v87
	v_fma_f32 v90, -v86, v89, v88
	v_fmac_f32_e32 v89, v90, v87
	v_fma_f32 v86, -v86, v89, v88
	v_div_fmas_f32 v86, v86, v87, v89
	v_div_fixup_f32 v86, v86, v66, 1.0
	v_mul_f32_e32 v88, v3, v86
	v_mul_f32_e32 v87, v2, v86
	v_rndne_f32_e32 v88, v88
	v_mul_f32_e32 v89, v4, v86
	v_mul_f32_e32 v90, v5, v86
	v_rndne_f32_e32 v87, v87
	v_cvt_i32_f32_e32 v88, v88
	v_rndne_f32_e32 v89, v89
	v_rndne_f32_e32 v90, v90
	v_cvt_i32_f32_e32 v87, v87
	v_cvt_i32_f32_sdwa v89, v89 dst_sel:WORD_1 dst_unused:UNUSED_PAD src0_sel:DWORD
	v_cvt_i32_f32_e32 v90, v90
	v_lshlrev_b32_e32 v88, 8, v88
	v_and_b32_e32 v88, 0xff00, v88
	v_and_b32_e32 v89, 0xff0000, v89
	v_perm_b32 v87, v90, v87, s84
	v_or3_b32 v87, v87, v88, v89
	v_mul_f32_e32 v88, v7, v86
	global_store_dword v[84:85], v87, off
	v_mul_f32_e32 v87, v6, v86
	v_rndne_f32_e32 v88, v88
	v_mul_f32_e32 v89, v8, v86
	v_mul_f32_e32 v90, v9, v86
	v_rndne_f32_e32 v87, v87
	v_cvt_i32_f32_e32 v88, v88
	v_rndne_f32_e32 v89, v89
	v_rndne_f32_e32 v90, v90
	v_cvt_i32_f32_e32 v87, v87
	v_cvt_i32_f32_sdwa v89, v89 dst_sel:WORD_1 dst_unused:UNUSED_PAD src0_sel:DWORD
	v_cvt_i32_f32_e32 v90, v90
	v_lshlrev_b32_e32 v88, 8, v88
	v_and_b32_e32 v88, 0xff00, v88
	v_and_b32_e32 v89, 0xff0000, v89
	v_perm_b32 v87, v90, v87, s84
	v_or3_b32 v87, v87, v88, v89
	v_mul_f32_e32 v88, v11, v86
	global_store_dword v[84:85], v87, off offset:256
	v_mul_f32_e32 v87, v10, v86
	v_rndne_f32_e32 v88, v88
	v_mul_f32_e32 v89, v12, v86
	v_mul_f32_e32 v90, v13, v86
	v_rndne_f32_e32 v87, v87
	v_cvt_i32_f32_e32 v88, v88
	v_rndne_f32_e32 v89, v89
	v_rndne_f32_e32 v90, v90
	v_cvt_i32_f32_e32 v87, v87
	v_cvt_i32_f32_sdwa v89, v89 dst_sel:WORD_1 dst_unused:UNUSED_PAD src0_sel:DWORD
	v_cvt_i32_f32_e32 v90, v90
	v_lshlrev_b32_e32 v88, 8, v88
	v_and_b32_e32 v88, 0xff00, v88
	v_and_b32_e32 v89, 0xff0000, v89
	v_perm_b32 v87, v90, v87, s84
	v_or3_b32 v87, v87, v88, v89
	v_mul_f32_e32 v88, v15, v86
	global_store_dword v[84:85], v87, off offset:512
	v_mul_f32_e32 v87, v14, v86
	v_rndne_f32_e32 v88, v88
	v_mul_f32_e32 v89, v16, v86
	v_mul_f32_e32 v86, v17, v86
	v_rndne_f32_e32 v87, v87
	v_cvt_i32_f32_e32 v88, v88
	v_rndne_f32_e32 v89, v89
	v_rndne_f32_e32 v86, v86
	v_cvt_i32_f32_e32 v87, v87
	v_cvt_i32_f32_sdwa v89, v89 dst_sel:WORD_1 dst_unused:UNUSED_PAD src0_sel:DWORD
	v_cvt_i32_f32_e32 v86, v86
	v_lshlrev_b32_e32 v88, 8, v88
	v_and_b32_e32 v88, 0xff00, v88
	v_and_b32_e32 v89, 0xff0000, v89
	v_perm_b32 v86, v86, v87, s84
	v_or3_b32 v86, v86, v88, v89
	global_store_dword v[84:85], v86, off offset:768
	s_and_saveexec_b64 s[2:3], s[40:41]
	s_cbranch_execz .LBB0_1276
	s_lshl_b64 s[10:11], s[10:11], 2
	s_add_u32 s10, s25, s10
	s_addc_u32 s11, s45, s11
	global_store_dword v67, v66, s[10:11]
	s_branch .Lmy_ln2d_tail9
